# pool staging loads batched, GEMM prologue full drains removed (FFN-up, merge)
# baseline (speedup 1.0000x reference)
; #define PG8_WAIT_V(n) asm volatile("s_waitcnt vmcnt(" #n ")" ::: "memory")
; #define PG8_BAR __builtin_amdgcn_s_barrier()
; template <class Epi, class Sched, bool ALIGN_EPI = false, bool SP2 = false, bool F8 = false>
; __device__ __forceinline__ void gemm_phase(PG8_LAS unsigned char* lds, const Gemm g, const Sched& S, const Epi& E) {
;     ...
;         PG8_STAGE(PG8_SB(1, 0), cB + kstep, voffB); PG8_STAGE(PG8_SA(1, 0), cA + kstep, voffA); PG8_STAGE(PG8_SB(1, 1), cB + hstep + kstep, voffB);
;         PG8_WAIT_V(6); PG8_BAR;
;     } else {
;         PG8_STAGE(PG8_SB(0, 0), cB, voffB); PG8_STAGE(PG8_SA(0, 0), cA, voffA); PG8_STAGE(PG8_SB(0, 1), cB + hstep, voffB); PG8_STAGE(PG8_SA(0, 1), cA + hstep, voffA);
;         if (wr == 1) PG8_BAR;
;         PG8_WAIT_V(4); PG8_BAR;
;         PG8_STAGE(PG8_SB(1, 0), cB + kstep, voffB); PG8_STAGE(PG8_SA(1, 0), cA + kstep, voffA); PG8_STAGE(PG8_SB(1, 1), cB + hstep + kstep, voffB);
;         PG8_WAIT_V(6); PG8_BAR;
.LBB0_291:
	s_lshl_b32 s3, s3, 5
	s_and_b32 s49, s3, 0x60
	s_lshl_b32 s48, s6, 6
	s_lshl_b32 s8, s6, 13
	s_lshl_b32 s9, s49, 7
	s_add_u32 s6, s18, 0x2000
	v_mov_b32_e32 v137, v3
	s_addc_u32 s7, s19, 0
	v_mov_b32_e32 v133, v3
	s_add_i32 m0, s40, 0x18000
	v_lshl_add_u64 v[12:13], s[6:7], 0, v[136:137]
	s_waitcnt vmcnt(2)
	s_barrier
	global_load_lds_dwordx4 v[12:13], off
	v_lshl_add_u64 v[12:13], s[6:7], 0, v[132:133]
	v_readlane_b32 s6, v254, 49
	v_mov_b32_e32 v139, v3
	s_add_i32 m0, s40, 0x1a000
	v_readlane_b32 s7, v254, 50
	s_add_i32 s50, s40, 0x8000
	v_mov_b32_e32 v135, v3
	global_load_lds_dwordx4 v[12:13], off
	v_lshl_add_u64 v[12:13], s[6:7], 0, v[138:139]
	s_mov_b32 m0, s50
	s_add_i32 s52, s40, 0xa000
	global_load_lds_dwordx4 v[12:13], off
	v_lshl_add_u64 v[12:13], s[6:7], 0, v[134:135]
	s_add_u32 s6, s18, 0x82000
	s_mov_b32 m0, s52
	s_addc_u32 s7, s19, 0
	global_load_lds_dwordx4 v[12:13], off
	s_add_i32 m0, s40, 0x1c000
	v_lshl_add_u64 v[12:13], s[6:7], 0, v[136:137]
	global_load_lds_dwordx4 v[12:13], off
	v_lshl_add_u64 v[12:13], s[6:7], 0, v[132:133]
	s_add_i32 m0, s40, 0x1e000
	v_and_b32_e32 v151, 15, v2
	global_load_lds_dwordx4 v[12:13], off
	v_lshrrev_b32_e32 v12, 1, v2
	v_and_b32_e32 v13, 24, v12
	v_lshlrev_b32_e32 v12, 6, v151
	v_lshlrev_b32_e32 v2, 2, v2
	v_lshl_or_b32 v14, v13, 1, v12
	v_and_b32_e32 v2, 32, v2
	v_bitop3_b32 v15, v14, s8, v2 bitop3:0xde
	v_bitop3_b32 v153, v14, s9, v2 bitop3:0xde
	v_add3_u32 v2, v10, v11, v8
	s_cmpk_lt_u32 s2, 0x100
	v_and_or_b32 v14, s3, 32, v13
	v_add_lshl_u32 v2, v2, v9, 1
	s_mov_b64 s[2:3], 0x82000
	v_lshl_add_u64 v[140:141], v[2:3], 0, s[2:3]
	v_add3_u32 v2, v6, v7, v4
	s_waitcnt vmcnt(6)
	v_add_lshl_u32 v2, v2, v5, 1
	v_or_b32_e32 v16, 0x800, v12
	v_or_b32_e32 v18, 0xc00, v12
	v_lshl_add_u64 v[142:143], v[2:3], 0, s[2:3]
	v_readlane_b32 s2, v254, 43
	v_readlane_b32 s16, v254, 47
	s_cselect_b64 s[6:7], -1, 0
	s_mov_b32 s53, 0
	v_add_u32_e32 v155, 0, v15
	v_lshlrev_b32_e32 v2, 1, v12
	v_lshlrev_b32_e32 v144, 1, v14
	v_lshlrev_b32_e32 v146, 1, v16
	v_lshlrev_b32_e32 v148, 1, v18
	v_readlane_b32 s54, v254, 40
	s_mov_b32 s55, s2
	v_readlane_b32 s17, v254, 48
	s_barrier
	v_readlane_b32 s3, v254, 44
	s_branch .LBB0_294

; #define LAS __attribute__((address_space(3)))
; __device__ __forceinline__ float bflo(unsigned w) { return __uint_as_float(w << 16); }
; __device__ __forceinline__ float bfhi(unsigned w) { return __uint_as_float(w & 0xffff0000u); }
; __device__ __forceinline__ void pool_units(LAS unsigned char* lds, const bf16* PROJ, const bf16* WPT, bf16* YP, int first, int stride, int nunits) {
;     ...
;         for (int idx = tid; idx < 79 * 24; idx += 512) { const int rr = idx / 24, cq = idx - rr * 24; const int srel = s0 - 15 + rr;
;             v4u x = (v4u){0u, 0u, 0u, 0u}; if (srel >= 0) x = *(const v4u*)(PROJ + (size_t)(t0 - 15 + rr) * NPROJ + C_PU + gp * 192 + cq * 8);
;             *(LAS f32x4*)(U + rr * 192 + cq * 8) = (f32x4){bflo(x.x), bfhi(x.x), bflo(x.y), bfhi(x.y)}; *(LAS f32x4*)(U + rr * 192 + cq * 8 + 4) = (f32x4){bflo(x.z), bfhi(x.z), bflo(x.w), bfhi(x.w)}; }
.LBB0_597:
	s_lshl_b32 s8, s40, 4
	s_and_b32 s41, s8, 0x7c0
	s_and_saveexec_b64 s[6:7], s[2:3]
	s_cbranch_execz .LBB0_602
	s_and_b32 s13, s8, 0xffffffc0
	s_sub_i32 s12, 14, s41
	s_add_i32 s13, s13, -15
	v_mov_b32_e32 v2, v196
	v_mov_b32_e32 v153, v195
	v_mov_b32_e32 v158, 0
	v_mov_b32_e32 v159, 0
	v_mov_b32_e32 v160, 0
	v_mov_b32_e32 v161, 0
	v_mov_b32_e32 v162, 0
	v_mov_b32_e32 v163, 0
	v_mov_b32_e32 v164, 0
	v_mov_b32_e32 v165, 0
	v_mov_b32_e32 v166, 0
	v_mov_b32_e32 v167, 0
	v_mov_b32_e32 v168, 0
	v_mov_b32_e32 v169, 0
	v_mov_b32_e32 v170, 0
	v_mov_b32_e32 v171, 0
	v_mov_b32_e32 v172, 0
	v_mov_b32_e32 v173, 0
	v_mul_hi_i32 v148, v153, s96
	v_lshrrev_b32_e32 v149, 31, v148
	v_ashrrev_i32_e32 v148, 2, v148
	v_add_u32_e32 v154, v148, v149
	v_cmp_lt_i32_e32 vcc, s12, v154
	s_and_saveexec_b64 s[10:11], vcc
	s_cbranch_execz .Lpl1_sk0
	v_add_u32_e32 v150, s13, v154
	v_mov_b64_e32 v[148:149], s[0:1]
	v_mad_i64_i32 v[148:149], s[44:45], v150, s77, v[148:149]
	v_mad_u64_u32 v[150:151], s[44:45], v154, s37, v[2:3]
	v_ashrrev_i32_e32 v151, 31, v150
	v_lshl_add_u64 v[148:149], v[150:151], 1, v[148:149]
	global_load_dwordx4 v[158:161], v[148:149], off offset:2560
.Lpl1_sk0:
	s_or_b64 exec, exec, s[10:11]
	v_add_u32_e32 v2, 0x1000, v2
	v_add_u32_e32 v153, 0x200, v153
	v_mul_hi_i32 v148, v153, s96
	v_lshrrev_b32_e32 v149, 31, v148
	v_ashrrev_i32_e32 v148, 2, v148
	v_add_u32_e32 v154, v148, v149
	v_cmp_lt_i32_e32 vcc, s12, v154
	s_and_saveexec_b64 s[10:11], vcc
	s_cbranch_execz .Lpl1_sk1
	v_add_u32_e32 v150, s13, v154
	v_mov_b64_e32 v[148:149], s[0:1]
	v_mad_i64_i32 v[148:149], s[44:45], v150, s77, v[148:149]
	v_mad_u64_u32 v[150:151], s[44:45], v154, s37, v[2:3]
	v_ashrrev_i32_e32 v151, 31, v150
	v_lshl_add_u64 v[148:149], v[150:151], 1, v[148:149]
	global_load_dwordx4 v[162:165], v[148:149], off offset:2560
.Lpl1_sk1:
	s_or_b64 exec, exec, s[10:11]
	v_add_u32_e32 v2, 0x1000, v2
	v_add_u32_e32 v153, 0x200, v153
	v_mul_hi_i32 v148, v153, s96
	v_lshrrev_b32_e32 v149, 31, v148
	v_ashrrev_i32_e32 v148, 2, v148
	v_add_u32_e32 v154, v148, v149
	v_cmp_lt_i32_e32 vcc, s12, v154
	s_and_saveexec_b64 s[10:11], vcc
	s_cbranch_execz .Lpl1_sk2
	v_add_u32_e32 v150, s13, v154
	v_mov_b64_e32 v[148:149], s[0:1]
	v_mad_i64_i32 v[148:149], s[44:45], v150, s77, v[148:149]
	v_mad_u64_u32 v[150:151], s[44:45], v154, s37, v[2:3]
	v_ashrrev_i32_e32 v151, 31, v150
	v_lshl_add_u64 v[148:149], v[150:151], 1, v[148:149]
	global_load_dwordx4 v[166:169], v[148:149], off offset:2560
.Lpl1_sk2:
	s_or_b64 exec, exec, s[10:11]
	v_add_u32_e32 v2, 0x1000, v2
	v_add_u32_e32 v153, 0x200, v153
	v_cmp_gt_i32_e32 vcc, 0x768, v153
	s_and_saveexec_b64 s[8:9], vcc
	v_mul_hi_i32 v148, v153, s96
	v_lshrrev_b32_e32 v149, 31, v148
	v_ashrrev_i32_e32 v148, 2, v148
	v_add_u32_e32 v154, v148, v149
	v_cmp_lt_i32_e32 vcc, s12, v154
	s_and_saveexec_b64 s[10:11], vcc
	s_cbranch_execz .Lpl1_sk3
	v_add_u32_e32 v150, s13, v154
	v_mov_b64_e32 v[148:149], s[0:1]
	v_mad_i64_i32 v[148:149], s[44:45], v150, s77, v[148:149]
	v_mad_u64_u32 v[150:151], s[44:45], v154, s37, v[2:3]
	v_ashrrev_i32_e32 v151, 31, v150
	v_lshl_add_u64 v[148:149], v[150:151], 1, v[148:149]
	global_load_dwordx4 v[170:173], v[148:149], off offset:2560
.Lpl1_sk3:
	s_or_b64 exec, exec, s[10:11]
	s_waitcnt vmcnt(0)
	v_lshlrev_b32_e32 v228, 16, v170
	v_and_b32_e32 v229, 0xffff0000, v170
	v_lshlrev_b32_e32 v230, 16, v171
	v_and_b32_e32 v231, 0xffff0000, v171
	v_lshlrev_b32_e32 v232, 16, v172
	v_and_b32_e32 v233, 0xffff0000, v172
	v_lshlrev_b32_e32 v234, 16, v173
	v_and_b32_e32 v235, 0xffff0000, v173
	ds_write_b128 v197, v[228:231] offset:49152
	ds_write_b128 v197, v[232:235] offset:49168
	s_or_b64 exec, exec, s[8:9]
	v_lshlrev_b32_e32 v228, 16, v158
	v_and_b32_e32 v229, 0xffff0000, v158
	v_lshlrev_b32_e32 v230, 16, v159
	v_and_b32_e32 v231, 0xffff0000, v159
	v_lshlrev_b32_e32 v232, 16, v160
	v_and_b32_e32 v233, 0xffff0000, v160
	v_lshlrev_b32_e32 v234, 16, v161
	v_and_b32_e32 v235, 0xffff0000, v161
	ds_write_b128 v197, v[228:231]
	ds_write_b128 v197, v[232:235] offset:16
	v_lshlrev_b32_e32 v228, 16, v162
	v_and_b32_e32 v229, 0xffff0000, v162
	v_lshlrev_b32_e32 v230, 16, v163
	v_and_b32_e32 v231, 0xffff0000, v163
	v_lshlrev_b32_e32 v232, 16, v164
	v_and_b32_e32 v233, 0xffff0000, v164
	v_lshlrev_b32_e32 v234, 16, v165
	v_and_b32_e32 v235, 0xffff0000, v165
	ds_write_b128 v197, v[228:231] offset:16384
	ds_write_b128 v197, v[232:235] offset:16400
	v_lshlrev_b32_e32 v228, 16, v166
	v_and_b32_e32 v229, 0xffff0000, v166
	v_lshlrev_b32_e32 v230, 16, v167
	v_and_b32_e32 v231, 0xffff0000, v167
	v_lshlrev_b32_e32 v232, 16, v168
	v_and_b32_e32 v233, 0xffff0000, v168
	v_lshlrev_b32_e32 v234, 16, v169
	v_and_b32_e32 v235, 0xffff0000, v169
	ds_write_b128 v197, v[228:231] offset:32768
	ds_write_b128 v197, v[232:235] offset:32784

; #define LAS __attribute__((address_space(3)))
; __device__ __forceinline__ float bflo(unsigned w) { return __uint_as_float(w << 16); }
; __device__ __forceinline__ float bfhi(unsigned w) { return __uint_as_float(w & 0xffff0000u); }
; __device__ __forceinline__ void pool_units(LAS unsigned char* lds, const bf16* PROJ, const bf16* WPT, bf16* YP, int first, int stride, int nunits) {
;     ...
;         for (int idx = tid; idx < 79 * 24; idx += 512) { const int rr = idx / 24, cq = idx - rr * 24; const int srel = s0 - 15 + rr;
;             v4u x = (v4u){0u, 0u, 0u, 0u}; if (srel >= 0) x = *(const v4u*)(PROJ + (size_t)(t0 - 15 + rr) * NPROJ + C_PU + gp * 192 + cq * 8);
;             *(LAS f32x4*)(U + rr * 192 + cq * 8) = (f32x4){bflo(x.x), bfhi(x.x), bflo(x.y), bfhi(x.y)}; *(LAS f32x4*)(U + rr * 192 + cq * 8 + 4) = (f32x4){bflo(x.z), bfhi(x.z), bflo(x.w), bfhi(x.w)}; }
.LBB0_627:
	s_lshl_b32 s8, s25, 4
	s_and_b32 s26, s8, 0x7c0
	s_and_saveexec_b64 s[0:1], s[4:5]
	s_cbranch_execz .LBB0_632
	s_and_b32 s13, s8, 0xffffffc0
	s_sub_i32 s12, 14, s26
	s_add_i32 s13, s13, -15
	v_readlane_b32 s40, v255, 1
	v_readlane_b32 s41, v255, 2
	v_mov_b32_e32 v2, v195
	v_mov_b32_e32 v153, v194
	v_mov_b32_e32 v158, 0
	v_mov_b32_e32 v159, 0
	v_mov_b32_e32 v160, 0
	v_mov_b32_e32 v161, 0
	v_mov_b32_e32 v162, 0
	v_mov_b32_e32 v163, 0
	v_mov_b32_e32 v164, 0
	v_mov_b32_e32 v165, 0
	v_mov_b32_e32 v166, 0
	v_mov_b32_e32 v167, 0
	v_mov_b32_e32 v168, 0
	v_mov_b32_e32 v169, 0
	v_mov_b32_e32 v170, 0
	v_mov_b32_e32 v171, 0
	v_mov_b32_e32 v172, 0
	v_mov_b32_e32 v173, 0
	v_mul_hi_i32 v148, v153, s96
	v_lshrrev_b32_e32 v149, 31, v148
	v_ashrrev_i32_e32 v148, 2, v148
	v_add_u32_e32 v154, v148, v149
	v_cmp_lt_i32_e32 vcc, s12, v154
	s_and_saveexec_b64 s[10:11], vcc
	s_cbranch_execz .Lpl2_sk0
	v_add_u32_e32 v150, s13, v154
	v_mov_b64_e32 v[148:149], s[40:41]
	v_mad_i64_i32 v[148:149], s[44:45], v150, s77, v[148:149]
	v_mad_u64_u32 v[150:151], s[44:45], v154, s37, v[2:3]
	v_ashrrev_i32_e32 v151, 31, v150
	v_lshl_add_u64 v[148:149], v[150:151], 1, v[148:149]
	global_load_dwordx4 v[158:161], v[148:149], off offset:2560
.Lpl2_sk0:
	s_or_b64 exec, exec, s[10:11]
	v_add_u32_e32 v2, 0x1000, v2
	v_add_u32_e32 v153, 0x200, v153
	v_mul_hi_i32 v148, v153, s96
	v_lshrrev_b32_e32 v149, 31, v148
	v_ashrrev_i32_e32 v148, 2, v148
	v_add_u32_e32 v154, v148, v149
	v_cmp_lt_i32_e32 vcc, s12, v154
	s_and_saveexec_b64 s[10:11], vcc
	s_cbranch_execz .Lpl2_sk1
	v_add_u32_e32 v150, s13, v154
	v_mov_b64_e32 v[148:149], s[40:41]
	v_mad_i64_i32 v[148:149], s[44:45], v150, s77, v[148:149]
	v_mad_u64_u32 v[150:151], s[44:45], v154, s37, v[2:3]
	v_ashrrev_i32_e32 v151, 31, v150
	v_lshl_add_u64 v[148:149], v[150:151], 1, v[148:149]
	global_load_dwordx4 v[162:165], v[148:149], off offset:2560
.Lpl2_sk1:
	s_or_b64 exec, exec, s[10:11]
	v_add_u32_e32 v2, 0x1000, v2
	v_add_u32_e32 v153, 0x200, v153
	v_mul_hi_i32 v148, v153, s96
	v_lshrrev_b32_e32 v149, 31, v148
	v_ashrrev_i32_e32 v148, 2, v148
	v_add_u32_e32 v154, v148, v149
	v_cmp_lt_i32_e32 vcc, s12, v154
	s_and_saveexec_b64 s[10:11], vcc
	s_cbranch_execz .Lpl2_sk2
	v_add_u32_e32 v150, s13, v154
	v_mov_b64_e32 v[148:149], s[40:41]
	v_mad_i64_i32 v[148:149], s[44:45], v150, s77, v[148:149]
	v_mad_u64_u32 v[150:151], s[44:45], v154, s37, v[2:3]
	v_ashrrev_i32_e32 v151, 31, v150
	v_lshl_add_u64 v[148:149], v[150:151], 1, v[148:149]
	global_load_dwordx4 v[166:169], v[148:149], off offset:2560
.Lpl2_sk2:
	s_or_b64 exec, exec, s[10:11]
	v_add_u32_e32 v2, 0x1000, v2
	v_add_u32_e32 v153, 0x200, v153
	v_cmp_gt_i32_e32 vcc, 0x768, v153
	s_and_saveexec_b64 s[8:9], vcc
	v_mul_hi_i32 v148, v153, s96
	v_lshrrev_b32_e32 v149, 31, v148
	v_ashrrev_i32_e32 v148, 2, v148
	v_add_u32_e32 v154, v148, v149
	v_cmp_lt_i32_e32 vcc, s12, v154
	s_and_saveexec_b64 s[10:11], vcc
	s_cbranch_execz .Lpl2_sk3
	v_add_u32_e32 v150, s13, v154
	v_mov_b64_e32 v[148:149], s[40:41]
	v_mad_i64_i32 v[148:149], s[44:45], v150, s77, v[148:149]
	v_mad_u64_u32 v[150:151], s[44:45], v154, s37, v[2:3]
	v_ashrrev_i32_e32 v151, 31, v150
	v_lshl_add_u64 v[148:149], v[150:151], 1, v[148:149]
	global_load_dwordx4 v[170:173], v[148:149], off offset:2560
.Lpl2_sk3:
	s_or_b64 exec, exec, s[10:11]
	s_waitcnt vmcnt(0)
	v_lshlrev_b32_e32 v228, 16, v170
	v_and_b32_e32 v229, 0xffff0000, v170
	v_lshlrev_b32_e32 v230, 16, v171
	v_and_b32_e32 v231, 0xffff0000, v171
	v_lshlrev_b32_e32 v232, 16, v172
	v_and_b32_e32 v233, 0xffff0000, v172
	v_lshlrev_b32_e32 v234, 16, v173
	v_and_b32_e32 v235, 0xffff0000, v173
	ds_write_b128 v196, v[228:231] offset:49152
	ds_write_b128 v196, v[232:235] offset:49168
	s_or_b64 exec, exec, s[8:9]
	v_lshlrev_b32_e32 v228, 16, v158
	v_and_b32_e32 v229, 0xffff0000, v158
	v_lshlrev_b32_e32 v230, 16, v159
	v_and_b32_e32 v231, 0xffff0000, v159
	v_lshlrev_b32_e32 v232, 16, v160
	v_and_b32_e32 v233, 0xffff0000, v160
	v_lshlrev_b32_e32 v234, 16, v161
	v_and_b32_e32 v235, 0xffff0000, v161
	ds_write_b128 v196, v[228:231]
	ds_write_b128 v196, v[232:235] offset:16
	v_lshlrev_b32_e32 v228, 16, v162
	v_and_b32_e32 v229, 0xffff0000, v162
	v_lshlrev_b32_e32 v230, 16, v163
	v_and_b32_e32 v231, 0xffff0000, v163
	v_lshlrev_b32_e32 v232, 16, v164
	v_and_b32_e32 v233, 0xffff0000, v164
	v_lshlrev_b32_e32 v234, 16, v165
	v_and_b32_e32 v235, 0xffff0000, v165
	ds_write_b128 v196, v[228:231] offset:16384
	ds_write_b128 v196, v[232:235] offset:16400
	v_lshlrev_b32_e32 v228, 16, v166
	v_and_b32_e32 v229, 0xffff0000, v166
	v_lshlrev_b32_e32 v230, 16, v167
	v_and_b32_e32 v231, 0xffff0000, v167
	v_lshlrev_b32_e32 v232, 16, v168
	v_and_b32_e32 v233, 0xffff0000, v168
	v_lshlrev_b32_e32 v234, 16, v169
	v_and_b32_e32 v235, 0xffff0000, v169
	ds_write_b128 v196, v[228:231] offset:32768
	ds_write_b128 v196, v[232:235] offset:32784

; #define PG8_WAIT_V(n) asm volatile("s_waitcnt vmcnt(" #n ")" ::: "memory")
; #define PG8_BAR __builtin_amdgcn_s_barrier()
; template <class Epi, class Sched, bool ALIGN_EPI = false, bool SP2 = false, bool F8 = false>
; __device__ __forceinline__ void gemm_phase(PG8_LAS unsigned char* lds, const Gemm g, const Sched& S, const Epi& E) {
;     ...
;     f32x4 acc[2][2][4][2];
; #pragma unroll
;     for (int a = 0; a < 2; ++a)
; #pragma unroll
;         for (int b = 0; b < 2; ++b)
; #pragma unroll
;             for (int m = 0; m < 4; ++m)
; #pragma unroll
;                 for (int n = 0; n < 2; ++n) acc[a][b][m][n] = (f32x4){0.f, 0.f, 0.f, 0.f};
;     bf16x8 At[4][2], B0[2][2], B1[2][2]; i32x8 At8[4], B08[2], B18[2];
;     const char* cA = (const char*)g.A + (size_t)cur.pm * tstep + (size_t)cur.seg * g.segA; const char* cB = (const char*)g.Bt + (size_t)cur.pn * tstep + (size_t)cur.seg * g.segB;
;     S.a_ready(cur);
;     if constexpr (SP2) {
;         PG8_STAGE(PG8_SB(0, 0), cB, voffB); PG8_STAGE(PG8_SB(0, 1), cB + hstep, voffB); PG8_STAGE(PG8_SA(0, 0), cA, voffA); PG8_STAGE(PG8_SA(0, 1), cA + hstep, voffA);
;         if (wr == 1) PG8_BAR;
;         PG8_WAIT_V(2); PG8_BAR;
;         PG8_STAGE(PG8_SB(1, 0), cB + kstep, voffB); PG8_STAGE(PG8_SA(1, 0), cA + kstep, voffA); PG8_STAGE(PG8_SB(1, 1), cB + hstep + kstep, voffB);
;         PG8_WAIT_V(6); PG8_BAR;
;     } else {
;         PG8_STAGE(PG8_SB(0, 0), cB, voffB); PG8_STAGE(PG8_SA(0, 0), cA, voffA); PG8_STAGE(PG8_SB(0, 1), cB + hstep, voffB); PG8_STAGE(PG8_SA(0, 1), cA + hstep, voffA);
;         if (wr == 1) PG8_BAR;
;         PG8_WAIT_V(4); PG8_BAR;
;         PG8_STAGE(PG8_SB(1, 0), cB + kstep, voffB); PG8_STAGE(PG8_SA(1, 0), cA + kstep, voffA); PG8_STAGE(PG8_SB(1, 1), cB + hstep + kstep, voffB);
;         PG8_WAIT_V(6); PG8_BAR;
.LBB0_1300:
	v_and_b32_e32 v141, 15, v2
	v_lshrrev_b32_e32 v12, 1, v2
	s_lshl_b32 s1, s1, 5
	v_and_b32_e32 v143, 24, v12
	v_lshlrev_b32_e32 v140, 6, v141
	v_lshlrev_b32_e32 v2, 2, v2
	s_and_b32 s42, s1, 0x60
	s_lshl_b32 s31, s2, 6
	v_lshl_or_b32 v12, v143, 1, v140
	s_lshl_b32 s2, s2, 13
	v_and_b32_e32 v2, 32, v2
	s_lshl_b32 s1, s42, 7
	v_bitop3_b32 v14, v12, s2, v2 bitop3:0xde
	s_add_u32 s2, s14, 0x2000
	v_mov_b32_e32 v137, v3
	s_addc_u32 s3, s15, 0
	v_mov_b32_e32 v133, v3
	v_bitop3_b32 v145, v12, s1, v2 bitop3:0xde
	s_add_i32 m0, s25, 0x18000
	v_lshl_add_u64 v[12:13], s[2:3], 0, v[136:137]
	s_waitcnt vmcnt(2)
	s_barrier
	global_load_lds_dwordx4 v[12:13], off
	v_lshl_add_u64 v[12:13], s[2:3], 0, v[132:133]
	v_readlane_b32 s2, v254, 59
	v_mov_b32_e32 v139, v3
	s_add_i32 m0, s25, 0x1a000
	v_readlane_b32 s3, v254, 60
	s_add_i32 s45, s25, 0x8000
	v_mov_b32_e32 v135, v3
	global_load_lds_dwordx4 v[12:13], off
	v_lshl_add_u64 v[12:13], s[2:3], 0, v[138:139]
	s_mov_b32 m0, s45
	s_add_i32 s52, s25, 0xa000
	global_load_lds_dwordx4 v[12:13], off
	v_lshl_add_u64 v[12:13], s[2:3], 0, v[134:135]
	s_add_u32 s2, s14, 0x32000
	s_mov_b32 m0, s52
	s_addc_u32 s3, s15, 0
	global_load_lds_dwordx4 v[12:13], off
	s_add_i32 m0, s25, 0x1c000
	v_lshl_add_u64 v[12:13], s[2:3], 0, v[136:137]
	global_load_lds_dwordx4 v[12:13], off
	v_lshl_add_u64 v[12:13], s[2:3], 0, v[132:133]
	s_add_i32 m0, s25, 0x1e000
	v_add3_u32 v2, v10, v11, v8
	global_load_lds_dwordx4 v[12:13], off
	s_cmpk_lt_u32 s0, 0x100
	v_add_lshl_u32 v2, v2, v9, 1
	s_mov_b64 s[0:1], 0x32000
	s_waitcnt vmcnt(6)
	v_lshl_add_u64 v[146:147], v[2:3], 0, s[0:1]
	v_add3_u32 v2, v6, v7, v4
	v_add_lshl_u32 v2, v2, v5, 1
	v_mov_b32_e32 v4, 0
	v_readlane_b32 s6, v254, 57
	s_cselect_b64 s[10:11], -1, 0
	v_or_b32_e32 v142, 0x800, v140
	v_or_b32_e32 v144, 0xc00, v140
	v_lshl_add_u64 v[148:149], v[2:3], 0, s[0:1]
	s_mov_b32 s4, 0
	v_add_u32_e32 v228, 0, v14
	v_readlane_b32 s5, v254, 51
	v_readlane_b32 s26, v254, 54
	v_readlane_b32 s7, v254, 58
	s_mov_b32 s53, 0
	v_mov_b32_e32 v5, v4
	v_mov_b32_e32 v6, v4
	v_mov_b32_e32 v7, v4
	v_mov_b32_e32 v8, v4
	v_mov_b32_e32 v9, v4
	v_mov_b32_e32 v10, v4
	v_mov_b32_e32 v11, v4
	v_mov_b32_e32 v12, v4
	v_mov_b32_e32 v13, v4
	v_mov_b32_e32 v14, v4
	v_mov_b32_e32 v15, v4
	v_mov_b32_e32 v16, v4
	v_mov_b32_e32 v17, v4
	v_mov_b32_e32 v18, v4
	v_mov_b32_e32 v19, v4
	v_mov_b32_e32 v20, v4
	v_mov_b32_e32 v21, v4
	v_mov_b32_e32 v22, v4
	v_mov_b32_e32 v23, v4
	v_mov_b32_e32 v24, v4
	v_mov_b32_e32 v25, v4
	v_mov_b32_e32 v26, v4
	v_mov_b32_e32 v27, v4
	v_mov_b32_e32 v28, v4
	v_mov_b32_e32 v29, v4
	v_mov_b32_e32 v30, v4
	v_mov_b32_e32 v31, v4
	v_mov_b32_e32 v32, v4
	v_mov_b32_e32 v33, v4
	v_mov_b32_e32 v34, v4
	v_mov_b32_e32 v35, v4
	v_mov_b32_e32 v36, v4
	v_mov_b32_e32 v37, v4
	v_mov_b32_e32 v38, v4
	v_mov_b32_e32 v39, v4
	v_mov_b32_e32 v40, v4
	v_mov_b32_e32 v41, v4
	v_mov_b32_e32 v42, v4
	v_mov_b32_e32 v43, v4
	v_mov_b32_e32 v44, v4
	v_mov_b32_e32 v45, v4
	v_mov_b32_e32 v46, v4
	v_mov_b32_e32 v47, v4
	v_mov_b32_e32 v48, v4
	v_mov_b32_e32 v49, v4
	v_mov_b32_e32 v50, v4
	v_mov_b32_e32 v51, v4
	v_mov_b32_e32 v52, v4
	v_mov_b32_e32 v53, v4
	v_mov_b32_e32 v54, v4
	v_mov_b32_e32 v55, v4
	v_mov_b32_e32 v56, v4
	v_mov_b32_e32 v57, v4
	v_mov_b32_e32 v58, v4
	v_mov_b32_e32 v59, v4
	v_mov_b32_e32 v60, v4
	v_mov_b32_e32 v61, v4
	v_mov_b32_e32 v62, v4
	v_mov_b32_e32 v63, v4
	v_mov_b32_e32 v64, v4
	v_mov_b32_e32 v65, v4
	v_mov_b32_e32 v66, v4
	v_mov_b32_e32 v67, v4
	v_mov_b32_e32 v68, v4
	v_mov_b32_e32 v69, v4
	v_mov_b32_e32 v70, v4
	v_mov_b32_e32 v71, v4
	v_mov_b32_e32 v72, v4
	v_mov_b32_e32 v73, v4
	v_mov_b32_e32 v74, v4
	v_mov_b32_e32 v75, v4
	v_mov_b32_e32 v76, v4
	v_mov_b32_e32 v77, v4
	v_mov_b32_e32 v78, v4
	v_mov_b32_e32 v79, v4
	v_mov_b32_e32 v80, v4
	v_mov_b32_e32 v81, v4
	v_mov_b32_e32 v82, v4
	v_mov_b32_e32 v83, v4
	v_mov_b32_e32 v84, v4
	v_mov_b32_e32 v85, v4
	v_mov_b32_e32 v86, v4
	v_mov_b32_e32 v87, v4
	v_mov_b32_e32 v88, v4
	v_mov_b32_e32 v89, v4
	v_mov_b32_e32 v90, v4
	v_mov_b32_e32 v91, v4
	v_mov_b32_e32 v92, v4
	v_mov_b32_e32 v93, v4
	v_mov_b32_e32 v94, v4
	v_mov_b32_e32 v95, v4
	v_mov_b32_e32 v96, v4
	v_mov_b32_e32 v97, v4
	v_mov_b32_e32 v98, v4
	v_mov_b32_e32 v99, v4
	v_mov_b32_e32 v100, v4
	v_mov_b32_e32 v101, v4
	v_mov_b32_e32 v102, v4
	v_mov_b32_e32 v103, v4
	v_mov_b32_e32 v104, v4
	v_mov_b32_e32 v105, v4
	v_mov_b32_e32 v106, v4
	v_mov_b32_e32 v107, v4
	v_mov_b32_e32 v108, v4
	v_mov_b32_e32 v109, v4
	v_mov_b32_e32 v110, v4
	v_mov_b32_e32 v111, v4
	v_mov_b32_e32 v112, v4
	v_mov_b32_e32 v113, v4
	v_mov_b32_e32 v114, v4
	v_mov_b32_e32 v115, v4
	v_mov_b32_e32 v116, v4
	v_mov_b32_e32 v117, v4
	v_mov_b32_e32 v118, v4
	v_mov_b32_e32 v119, v4
	v_mov_b32_e32 v120, v4
	v_mov_b32_e32 v121, v4
	v_mov_b32_e32 v122, v4
	v_mov_b32_e32 v123, v4
	v_mov_b32_e32 v124, v4
	v_mov_b32_e32 v125, v4
	v_mov_b32_e32 v126, v4
	v_mov_b32_e32 v127, v4
	v_mov_b32_e32 v128, v4
	v_mov_b32_e32 v129, v4
	v_mov_b32_e32 v130, v4
	v_mov_b32_e32 v131, v4
	s_barrier
	s_branch .LBB0_1303
